# attention phase: flat->global, drop store drains at step end/top, K/V ring write moved to step end, chain setup counted wait
# baseline (speedup 1.0000x reference)
.LBB0_955:
	s_lshl_b32 s23, s46, 1
	s_lshr_b32 s25, 64, s23
	s_and_b32 s24, s2, 0xff
	s_add_i32 s25, s25, -1
	s_and_b32 s26, s25, s24
	s_sub_i32 s25, 6, s23
	s_lshr_b32 s24, s24, s25
	s_lshr_b32 s27, s24, 1
	s_lshl_b32 s28, -1, s23
	s_andn2_b32 s27, s27, s28
	s_or_b32 s28, s23, 1
	s_and_b32 s25, s24, 1
	s_lshr_b32 s24, s24, s28
	s_lshl_b32 s24, s24, 14
	s_lshl_b32 s28, s46, 9
	s_or_b32 s88, s24, s27
	s_lshl_b32 s24, s25, 2
	s_ashr_i32 s29, s28, 31
	s_xor_b64 s[86:87], s[84:85], -1
	s_add_i32 s24, s24, s10
	s_lshl_b64 s[28:29], s[28:29], 1
	s_add_u32 s27, s4, s28
	s_addc_u32 s29, s5, s29
	s_lshl_b32 s25, s25, 8
	s_add_u32 s28, s27, s25
	s_addc_u32 s29, s29, 0
	s_ashr_i32 s47, s46, 31
	s_lshl_b64 s[42:43], s[46:47], 2
	s_add_u32 s42, s62, s42
	s_addc_u32 s43, s63, s43
	global_load_dword v84, v239, s[42:43] offset:3072
	s_lshl_b32 s42, s46, 10
	s_ashr_i32 s43, s42, 31
	s_lshl_b64 s[42:43], s[42:43], 1
	s_add_u32 s25, s8, s42
	s_addc_u32 s27, s9, s43
	s_lshl_b32 s42, s24, 8
	s_add_u32 s90, s25, s42
	s_addc_u32 s91, s27, 0
	s_lshl_b32 s27, s26, 8
	v_or_b32_e32 v156, s27, v219
	v_lshlrev_b64 v[52:53], s23, v[156:157]
	v_or_b32_e32 v156, 16, v156
	s_mov_b32 s89, s65
	v_lshlrev_b64 v[66:67], s23, v[156:157]
	v_lshl_add_u64 v[168:169], v[158:159], 1, s[90:91]
	v_lshl_add_u64 v[52:53], v[52:53], 0, s[88:89]
	v_lshl_add_u64 v[66:67], v[66:67], 0, s[88:89]
	v_mad_u64_u32 v[64:65], s[42:43], v52, s20, v[168:169]
	v_mad_u64_u32 v[80:81], s[42:43], v66, s20, v[168:169]
	v_mov_b32_e32 v52, v65
	v_mov_b32_e32 v66, v81
	v_mad_u64_u32 v[52:53], s[42:43], v53, s20, v[52:53]
	v_mad_u64_u32 v[66:67], s[42:43], v67, s20, v[66:67]
	v_mov_b32_e32 v65, v52
	v_mov_b32_e32 v81, v66
	global_load_dwordx4 v[52:55], v[64:65], off offset:64
	global_load_dwordx4 v[56:59], v[64:65], off offset:128
	global_load_dwordx4 v[60:63], v[64:65], off offset:192
	global_load_dwordx4 v[68:71], v[80:81], off
	global_load_dwordx4 v[72:75], v[80:81], off offset:64
	global_load_dwordx4 v[76:79], v[80:81], off offset:128
	s_nop 0
	global_load_dwordx4 v[64:67], v[64:65], off
	s_nop 0
	global_load_dwordx4 v[80:83], v[80:81], off offset:192
	v_mov_b32_e32 v165, v157
	s_cmp_lg_u32 s26, 0
	v_lshl_add_u64 v[170:171], s[28:29], 0, v[164:165]
	s_cselect_b64 s[48:49], -1, 0
	s_cmp_eq_u32 s26, 0
	s_waitcnt vmcnt(8)
	v_readfirstlane_b32 s25, v84
	v_add_u32_e32 v84, 0xffffff80, v218
	v_add_u32_e32 v94, s27, v84
	s_cbranch_scc1 .LBB0_957
	v_ashrrev_i32_e32 v95, 31, v94
	v_lshlrev_b64 v[84:85], s23, v[94:95]
	v_lshl_add_u64 v[84:85], v[84:85], 0, s[88:89]
	v_mad_u64_u32 v[86:87], s[28:29], v84, s21, v[170:171]
	v_mov_b32_e32 v84, v87
	v_mad_u64_u32 v[84:85], s[28:29], v85, s21, v[84:85]
	v_mov_b32_e32 v87, v84
	global_load_dwordx4 v[88:91], v[86:87], off
	s_nop 0
	global_load_dwordx4 v[84:87], v[86:87], off offset:512
	s_branch .LBB0_958

.LBB0_967:
	s_cmp_lg_u32 s27, 0x1a400
	s_cselect_b64 s[46:47], -1, 0
	s_cmp_eq_u32 s27, 0x1a400
	v_lshl_add_u64 v[182:183], v[172:173], 0, s[92:93]
	s_cbranch_scc1 .LBB0_969
	v_lshl_add_u64 v[4:5], v[180:181], 0, s[92:93]
	v_lshl_add_u64 v[12:13], v[174:175], 0, s[92:93]
	v_lshl_add_u64 v[20:21], v[182:183], 0, 64
	v_lshl_add_u64 v[36:37], v[156:157], 0, s[92:93]
	v_lshlrev_b64 v[4:5], s23, v[4:5]
	v_lshlrev_b64 v[12:13], s23, v[12:13]
	v_lshlrev_b64 v[20:21], s23, v[20:21]
	v_lshlrev_b64 v[36:37], s23, v[36:37]
	v_lshl_add_u64 v[4:5], v[4:5], 0, s[88:89]
	v_lshl_add_u64 v[12:13], v[12:13], 0, s[88:89]
	v_lshl_add_u64 v[20:21], v[20:21], 0, s[88:89]
	v_lshl_add_u64 v[36:37], v[36:37], 0, s[88:89]
	v_mad_u64_u32 v[8:9], s[42:43], v4, s21, v[170:171]
	v_mad_u64_u32 v[16:17], s[42:43], v12, s21, v[170:171]
	v_mad_u64_u32 v[22:23], s[42:43], v20, s20, v[168:169]
	v_mad_u64_u32 v[38:39], s[42:43], v36, s20, v[168:169]
	v_mov_b32_e32 v4, v9
	v_mov_b32_e32 v12, v17
	v_mov_b32_e32 v20, v23
	v_mov_b32_e32 v36, v39
	v_mad_u64_u32 v[4:5], s[42:43], v5, s21, v[4:5]
	v_mad_u64_u32 v[12:13], s[42:43], v13, s21, v[12:13]
	v_mad_u64_u32 v[20:21], s[42:43], v21, s20, v[20:21]
	v_mad_u64_u32 v[36:37], s[42:43], v37, s20, v[36:37]
	v_mov_b32_e32 v9, v4
	v_mov_b32_e32 v17, v12
	v_mov_b32_e32 v23, v20
	v_mov_b32_e32 v39, v36
	global_load_dwordx4 v[4:7], v[8:9], off
	s_nop 0
	global_load_dwordx4 v[8:11], v[8:9], off offset:512
	s_nop 0
	global_load_dwordx4 v[12:15], v[16:17], off
	s_nop 0
	global_load_dwordx4 v[16:19], v[16:17], off offset:512
	s_nop 0
	global_load_dwordx4 v[32:35], v[22:23], off
	global_load_dwordx4 v[28:31], v[22:23], off offset:64
	global_load_dwordx4 v[24:27], v[22:23], off offset:128
	s_nop 0
	global_load_dwordx4 v[20:23], v[22:23], off offset:192
	s_nop 0
	global_load_dwordx4 v[48:51], v[38:39], off
	global_load_dwordx4 v[44:47], v[38:39], off offset:64
	global_load_dwordx4 v[40:43], v[38:39], off offset:128
	s_nop 0
	global_load_dwordx4 v[36:39], v[38:39], off offset:192
.LBB0_969:
	s_xor_b32 s60, s29, 2
	s_and_b32 s64, s60, 3
	s_mul_i32 s64, s64, 0x8c00
	v_add_u32_e32 v96, s64, v224
	ds_read_b128 v[84:87], v96
	ds_read_b128 v[88:91], v96 offset:64
	v_mov_b64_e32 v[150:151], s[50:51]
	v_mov_b64_e32 v[148:149], s[48:49]
	s_add_i32 s42, s60, s12
	s_and_b32 s42, s42, 3
	s_mul_i32 s42, s42, 0x8c00
	v_add_u32_e32 v100, s42, v225
	s_add_i32 s42, s60, s13
	s_waitcnt lgkmcnt(0)
	v_mfma_f32_16x16x32_bf16 v[84:87], v[84:87], v[64:67], v[148:151]
	s_and_b32 s42, s42, 3
	s_mul_i32 s42, s42, 0x8c00
	v_add_u32_e32 v108, s42, v226
	s_waitcnt lgkmcnt(0)
	v_mfma_f32_16x16x32_bf16 v[84:87], v[88:91], v[52:55], v[84:87]
	ds_read_b128 v[88:91], v96 offset:128
	ds_read_b128 v[92:95], v96 offset:4416
	s_add_i32 s42, s60, 1
	s_and_b32 s61, s42, 3
	s_mul_i32 s61, s61, 0x8c00
	v_add_u32_e32 v124, s61, v224
	s_add_i32 s42, s60, s14
	s_and_b32 s42, s42, 3
	s_waitcnt lgkmcnt(0)
	v_mfma_f32_16x16x32_bf16 v[84:87], v[88:91], v[56:59], v[84:87]
	ds_read_b128 v[88:91], v96 offset:192
	ds_read_b128 v[104:107], v108 offset:64
	s_mul_i32 s42, s42, 0x8c00
	v_add_u32_e32 v132, s42, v227
	s_add_i32 s42, s60, s15
	s_and_b32 s42, s42, 3
	s_mul_i32 s42, s42, 0x8c00
	s_waitcnt lgkmcnt(0)
	v_mfma_f32_16x16x32_bf16 v[140:143], v[88:91], v[60:63], v[84:87]
	ds_read_b128 v[112:115], v124 offset:64
	s_nop 1
	ds_read_b128 v[84:87], v96 offset:4352
	v_add_u32_e32 v152, s42, v228
	v_add_u32_e32 v167, s27, v224
	s_andn2_b64 vcc, exec, s[46:47]
	s_waitcnt lgkmcnt(0)
	v_mfma_f32_16x16x32_bf16 v[88:91], v[84:87], v[64:67], v[148:151]
	ds_read_b128 v[120:123], v124 offset:4416
	ds_read_b128 v[128:131], v132 offset:64
	ds_read_b128 v[136:139], v152 offset:64
	v_mfma_f32_16x16x32_bf16 v[84:87], v[84:87], v[68:71], v[148:151]
	ds_read_b128 v[184:187], v167 offset:64
	v_mfma_f32_16x16x32_bf16 v[88:91], v[92:95], v[52:55], v[88:91]
	v_mfma_f32_16x16x32_bf16 v[84:87], v[92:95], v[72:75], v[84:87]
	ds_read_b128 v[92:95], v96 offset:4480
	ds_read_b128 v[96:99], v96 offset:4544
	s_waitcnt lgkmcnt(0)
	v_mfma_f32_16x16x32_bf16 v[88:91], v[92:95], v[56:59], v[88:91]
	v_mfma_f32_16x16x32_bf16 v[92:95], v[92:95], v[76:79], v[84:87]
	s_waitcnt lgkmcnt(0)
	v_mfma_f32_16x16x32_bf16 v[84:87], v[96:99], v[60:63], v[88:91]
	s_nop 4
	ds_read_b128 v[88:91], v100
	v_mfma_f32_16x16x32_bf16 v[144:147], v[96:99], v[80:83], v[92:95]
	ds_read_b128 v[96:99], v100 offset:64
	s_waitcnt lgkmcnt(0)
	v_mfma_f32_16x16x32_bf16 v[92:95], v[88:91], v[64:67], v[148:151]
	v_mfma_f32_16x16x32_bf16 v[88:91], v[88:91], v[68:71], v[148:151]
	s_waitcnt lgkmcnt(0)
	v_mfma_f32_16x16x32_bf16 v[92:95], v[96:99], v[52:55], v[92:95]
	v_mfma_f32_16x16x32_bf16 v[88:91], v[96:99], v[72:75], v[88:91]
	ds_read_b128 v[96:99], v100 offset:128
	s_waitcnt lgkmcnt(0)
	v_mfma_f32_16x16x32_bf16 v[92:95], v[96:99], v[56:59], v[92:95]
	v_mfma_f32_16x16x32_bf16 v[88:91], v[96:99], v[76:79], v[88:91]
	ds_read_b128 v[96:99], v100 offset:192
	s_waitcnt lgkmcnt(0)
	v_mfma_f32_16x16x32_bf16 v[92:95], v[96:99], v[60:63], v[92:95]
	v_mfma_f32_16x16x32_bf16 v[88:91], v[96:99], v[80:83], v[88:91]
	ds_read_b128 v[96:99], v108
	s_waitcnt lgkmcnt(0)
	v_mfma_f32_16x16x32_bf16 v[100:103], v[96:99], v[64:67], v[148:151]
	v_mfma_f32_16x16x32_bf16 v[96:99], v[96:99], v[68:71], v[148:151]
	v_mfma_f32_16x16x32_bf16 v[100:103], v[104:107], v[52:55], v[100:103]
	v_mfma_f32_16x16x32_bf16 v[96:99], v[104:107], v[72:75], v[96:99]
	ds_read_b128 v[104:107], v108 offset:128
	s_waitcnt lgkmcnt(0)
	v_mfma_f32_16x16x32_bf16 v[100:103], v[104:107], v[56:59], v[100:103]
	v_mfma_f32_16x16x32_bf16 v[96:99], v[104:107], v[76:79], v[96:99]
	ds_read_b128 v[104:107], v108 offset:192
	s_waitcnt lgkmcnt(0)
	v_mfma_f32_16x16x32_bf16 v[100:103], v[104:107], v[60:63], v[100:103]
	v_mfma_f32_16x16x32_bf16 v[96:99], v[104:107], v[80:83], v[96:99]
	ds_read_b128 v[104:107], v124
	s_waitcnt lgkmcnt(0)
	v_mfma_f32_16x16x32_bf16 v[108:111], v[104:107], v[64:67], v[148:151]
	v_mfma_f32_16x16x32_bf16 v[104:107], v[104:107], v[68:71], v[148:151]
	v_mfma_f32_16x16x32_bf16 v[108:111], v[112:115], v[52:55], v[108:111]
	v_mfma_f32_16x16x32_bf16 v[104:107], v[112:115], v[72:75], v[104:107]
	ds_read_b128 v[112:115], v124 offset:128
	s_waitcnt lgkmcnt(0)
	v_mfma_f32_16x16x32_bf16 v[108:111], v[112:115], v[56:59], v[108:111]
	v_mfma_f32_16x16x32_bf16 v[104:107], v[112:115], v[76:79], v[104:107]
	ds_read_b128 v[112:115], v124 offset:192
	s_waitcnt lgkmcnt(0)
	v_mfma_f32_16x16x32_bf16 v[108:111], v[112:115], v[60:63], v[108:111]
	v_mfma_f32_16x16x32_bf16 v[104:107], v[112:115], v[80:83], v[104:107]
	ds_read_b128 v[112:115], v124 offset:4352
	s_waitcnt lgkmcnt(0)
	v_mfma_f32_16x16x32_bf16 v[116:119], v[112:115], v[64:67], v[148:151]
	v_mfma_f32_16x16x32_bf16 v[112:115], v[112:115], v[68:71], v[148:151]
	v_mfma_f32_16x16x32_bf16 v[116:119], v[120:123], v[52:55], v[116:119]
	v_mfma_f32_16x16x32_bf16 v[112:115], v[120:123], v[72:75], v[112:115]
	ds_read_b128 v[120:123], v124 offset:4480
	s_waitcnt lgkmcnt(0)
	v_mfma_f32_16x16x32_bf16 v[116:119], v[120:123], v[56:59], v[116:119]
	v_mfma_f32_16x16x32_bf16 v[112:115], v[120:123], v[76:79], v[112:115]
	ds_read_b128 v[120:123], v124 offset:4544
	s_waitcnt lgkmcnt(0)
	v_mfma_f32_16x16x32_bf16 v[116:119], v[120:123], v[60:63], v[116:119]
	v_mfma_f32_16x16x32_bf16 v[112:115], v[120:123], v[80:83], v[112:115]
	ds_read_b128 v[120:123], v132
	s_waitcnt lgkmcnt(0)
	v_mfma_f32_16x16x32_bf16 v[124:127], v[120:123], v[64:67], v[148:151]
	v_mfma_f32_16x16x32_bf16 v[120:123], v[120:123], v[68:71], v[148:151]
	v_mfma_f32_16x16x32_bf16 v[124:127], v[128:131], v[52:55], v[124:127]
	v_mfma_f32_16x16x32_bf16 v[120:123], v[128:131], v[72:75], v[120:123]
	ds_read_b128 v[128:131], v132 offset:128
	s_waitcnt lgkmcnt(0)
	v_mfma_f32_16x16x32_bf16 v[124:127], v[128:131], v[56:59], v[124:127]
	v_mfma_f32_16x16x32_bf16 v[120:123], v[128:131], v[76:79], v[120:123]
	ds_read_b128 v[128:131], v132 offset:192
	s_waitcnt lgkmcnt(0)
	v_mfma_f32_16x16x32_bf16 v[124:127], v[128:131], v[60:63], v[124:127]
	v_mfma_f32_16x16x32_bf16 v[120:123], v[128:131], v[80:83], v[120:123]
	ds_read_b128 v[128:131], v152
	s_waitcnt lgkmcnt(0)
	v_mfma_f32_16x16x32_bf16 v[132:135], v[128:131], v[64:67], v[148:151]
	v_mfma_f32_16x16x32_bf16 v[128:131], v[128:131], v[68:71], v[148:151]
	v_mfma_f32_16x16x32_bf16 v[132:135], v[136:139], v[52:55], v[132:135]
	v_mfma_f32_16x16x32_bf16 v[128:131], v[136:139], v[72:75], v[128:131]
	ds_read_b128 v[136:139], v152 offset:128
	s_waitcnt lgkmcnt(0)
	v_mfma_f32_16x16x32_bf16 v[132:135], v[136:139], v[56:59], v[132:135]
	v_mfma_f32_16x16x32_bf16 v[128:131], v[136:139], v[76:79], v[128:131]
	ds_read_b128 v[136:139], v152 offset:192
	s_waitcnt lgkmcnt(0)
	v_mfma_f32_16x16x32_bf16 v[132:135], v[136:139], v[60:63], v[132:135]
	v_mfma_f32_16x16x32_bf16 v[128:131], v[136:139], v[80:83], v[128:131]
	ds_read_b128 v[136:139], v167
	s_waitcnt lgkmcnt(0)
	v_mfma_f32_16x16x32_bf16 v[152:155], v[136:139], v[64:67], v[148:151]
	v_mfma_f32_16x16x32_bf16 v[136:139], v[136:139], v[68:71], v[148:151]
	v_mfma_f32_16x16x32_bf16 v[152:155], v[184:187], v[52:55], v[152:155]
	v_mfma_f32_16x16x32_bf16 v[136:139], v[184:187], v[72:75], v[136:139]
	ds_read_b128 v[184:187], v167 offset:128
	s_waitcnt lgkmcnt(0)
	v_mfma_f32_16x16x32_bf16 v[152:155], v[184:187], v[56:59], v[152:155]
	v_mfma_f32_16x16x32_bf16 v[136:139], v[184:187], v[76:79], v[136:139]
	ds_read_b128 v[184:187], v167 offset:192
	s_waitcnt lgkmcnt(0)
	v_mfma_f32_16x16x32_bf16 v[152:155], v[184:187], v[60:63], v[152:155]
	v_mfma_f32_16x16x32_bf16 v[136:139], v[184:187], v[80:83], v[136:139]
	ds_read_b128 v[184:187], v167 offset:4352
	s_waitcnt lgkmcnt(0)
	v_mfma_f32_16x16x32_bf16 v[148:151], v[184:187], v[68:71], v[148:151]
	ds_read_b128 v[184:187], v167 offset:4416
	s_waitcnt lgkmcnt(0)
	v_mfma_f32_16x16x32_bf16 v[148:151], v[184:187], v[72:75], v[148:151]
	ds_read_b128 v[184:187], v167 offset:4480
	s_waitcnt lgkmcnt(0)
	v_mfma_f32_16x16x32_bf16 v[148:151], v[184:187], v[76:79], v[148:151]
	ds_read_b128 v[184:187], v167 offset:4544
	v_cndmask_b32_e64 v167, 0, 1, s[46:47]
	v_cmp_ne_u32_e64 s[42:43], 1, v167
	s_waitcnt lgkmcnt(0)
	v_mfma_f32_16x16x32_bf16 v[148:151], v[184:187], v[80:83], v[148:151]
.LBB0_971:
	v_mov_b32_e32 v186, v220
	v_mov_b32_e32 v185, v165
	s_add_i32 s96, s26, s29
	v_cmp_gt_i32_e32 vcc, 1, v186
	v_cmp_lt_i32_e64 s[46:47], -1, v186
	s_cmp_gt_u32 s96, 1
	v_cndmask_b32_e32 v167, v245, v140, vcc
	v_cndmask_b32_e64 v152, v245, v152, s[46:47]
	v_cndmask_b32_e32 v144, v245, v144, vcc
	v_cndmask_b32_e64 v140, v245, v148, s[46:47]
	v_cmp_gt_i32_e32 vcc, 2, v186
	v_cmp_lt_i32_e64 s[46:47], 0, v186
	s_nop 0
	v_cndmask_b32_e32 v184, v245, v141, vcc
	v_cndmask_b32_e64 v148, v245, v153, s[46:47]
	v_cndmask_b32_e32 v145, v245, v145, vcc
	v_cndmask_b32_e64 v141, v245, v149, s[46:47]
	v_cmp_gt_i32_e32 vcc, 3, v186
	v_cmp_lt_i32_e64 s[46:47], 1, v186
	s_nop 0
	v_cndmask_b32_e32 v153, v245, v142, vcc
	v_cndmask_b32_e64 v149, v245, v154, s[46:47]
	v_cndmask_b32_e32 v146, v245, v146, vcc
	v_cndmask_b32_e64 v142, v245, v150, s[46:47]
	v_cmp_gt_i32_e32 vcc, 4, v186
	v_cmp_lt_i32_e64 s[46:47], 2, v186
	s_nop 0
	v_cndmask_b32_e32 v154, v245, v143, vcc
	v_cndmask_b32_e64 v150, v245, v155, s[46:47]
	v_cndmask_b32_e32 v147, v245, v147, vcc
	v_cndmask_b32_e64 v143, v245, v151, s[46:47]
	s_cbranch_scc1 .LBB0_973
	v_cmp_gt_i32_e32 vcc, 1, v185
	s_movk_i32 s46, 0x41
	s_nop 0
	v_cndmask_b32_e32 v167, v245, v167, vcc
	v_cmp_gt_i32_e32 vcc, 2, v185
	s_nop 1
	v_cndmask_b32_e32 v184, v245, v184, vcc
	v_cmp_gt_i32_e32 vcc, 3, v185
	s_nop 1
	v_cndmask_b32_e32 v153, v245, v153, vcc
	v_cmp_gt_i32_e32 vcc, 4, v185
	s_nop 1
	v_cndmask_b32_e32 v154, v245, v154, vcc
	v_cmp_lt_i32_e32 vcc, 16, v185
	s_nop 1
	v_cndmask_b32_e32 v84, v84, v245, vcc
	v_cndmask_b32_e32 v144, v144, v245, vcc
	v_cmp_lt_i32_e32 vcc, 17, v185
	s_nop 1
	v_cndmask_b32_e32 v85, v85, v245, vcc
	v_cndmask_b32_e32 v145, v145, v245, vcc
	v_cmp_lt_i32_e32 vcc, 18, v185
	s_nop 1
	v_cndmask_b32_e32 v86, v86, v245, vcc
	v_cndmask_b32_e32 v146, v146, v245, vcc
	v_cmp_lt_i32_e32 vcc, 19, v185
	s_nop 1
	v_cndmask_b32_e32 v87, v87, v245, vcc
	v_cndmask_b32_e32 v147, v147, v245, vcc
	v_cmp_lt_i32_e32 vcc, 32, v185
	s_nop 1
	v_cndmask_b32_e32 v92, v92, v245, vcc
	v_cndmask_b32_e32 v88, v88, v245, vcc
	v_cmp_lt_i32_e32 vcc, 33, v185
	s_nop 1
	v_cndmask_b32_e32 v93, v93, v245, vcc
	v_cndmask_b32_e32 v89, v89, v245, vcc
	v_cmp_lt_i32_e32 vcc, 34, v185
	s_nop 1
	v_cndmask_b32_e32 v94, v94, v245, vcc
	v_cndmask_b32_e32 v90, v90, v245, vcc
	v_cmp_lt_i32_e32 vcc, 35, v185
	s_nop 1
	v_cndmask_b32_e32 v95, v95, v245, vcc
	v_cndmask_b32_e32 v91, v91, v245, vcc
	v_cmp_lt_i32_e32 vcc, 48, v185
	s_nop 1
	v_cndmask_b32_e32 v100, v100, v245, vcc
	v_cndmask_b32_e32 v96, v96, v245, vcc
	v_cmp_lt_i32_e32 vcc, 49, v185
	s_nop 1
	v_cndmask_b32_e32 v101, v101, v245, vcc
	v_cndmask_b32_e32 v97, v97, v245, vcc
	v_cmp_lt_i32_e32 vcc, 50, v185
	s_nop 1
	v_cndmask_b32_e32 v102, v102, v245, vcc
	v_cndmask_b32_e32 v98, v98, v245, vcc
	v_cmp_lt_i32_e32 vcc, 51, v185
	s_nop 1
	v_cndmask_b32_e32 v103, v103, v245, vcc
	v_cndmask_b32_e32 v99, v99, v245, vcc
	v_cmp_lt_i32_e32 vcc, 64, v185
	s_nop 1
	v_cndmask_b32_e32 v108, v108, v245, vcc
	v_cndmask_b32_e32 v104, v104, v245, vcc
	v_cmp_lt_i32_e32 vcc, s46, v185
	s_movk_i32 s46, 0x42
	s_nop 0
	v_cndmask_b32_e32 v109, v109, v245, vcc
	v_cndmask_b32_e32 v105, v105, v245, vcc
	v_cmp_lt_i32_e32 vcc, s46, v185
	s_movk_i32 s46, 0x43
	s_nop 0
	v_cndmask_b32_e32 v110, v110, v245, vcc
	v_cndmask_b32_e32 v106, v106, v245, vcc
	v_cmp_lt_i32_e32 vcc, s46, v185
	s_movk_i32 s46, 0x50
	s_nop 0
	v_cndmask_b32_e32 v111, v111, v245, vcc
	v_cndmask_b32_e32 v107, v107, v245, vcc
	v_cmp_lt_i32_e32 vcc, s46, v185
	s_movk_i32 s46, 0x51
	s_nop 0
	v_cndmask_b32_e32 v116, v116, v245, vcc
	v_cndmask_b32_e32 v112, v112, v245, vcc
	v_cmp_lt_i32_e32 vcc, s46, v185
	s_movk_i32 s46, 0x52
	s_nop 0
	v_cndmask_b32_e32 v117, v117, v245, vcc
	v_cndmask_b32_e32 v113, v113, v245, vcc
	v_cmp_lt_i32_e32 vcc, s46, v185
	s_movk_i32 s46, 0x53
	s_nop 0
	v_cndmask_b32_e32 v118, v118, v245, vcc
	v_cndmask_b32_e32 v114, v114, v245, vcc
	v_cmp_lt_i32_e32 vcc, s46, v185
	s_movk_i32 s46, 0x60
	s_nop 0
	v_cndmask_b32_e32 v119, v119, v245, vcc
	v_cndmask_b32_e32 v115, v115, v245, vcc
	v_cmp_lt_i32_e32 vcc, s46, v185
	s_movk_i32 s46, 0x61
	s_nop 0
	v_cndmask_b32_e32 v124, v124, v245, vcc
	v_cndmask_b32_e32 v120, v120, v245, vcc
	v_cmp_lt_i32_e32 vcc, s46, v185
	s_movk_i32 s46, 0x62
	s_nop 0
	v_cndmask_b32_e32 v125, v125, v245, vcc
	v_cndmask_b32_e32 v121, v121, v245, vcc
	v_cmp_lt_i32_e32 vcc, s46, v185
	s_movk_i32 s46, 0x63
	s_nop 0
	v_cndmask_b32_e32 v126, v126, v245, vcc
	v_cndmask_b32_e32 v122, v122, v245, vcc
	v_cmp_lt_i32_e32 vcc, s46, v185
	s_movk_i32 s46, 0x70
	s_nop 0
	v_cndmask_b32_e32 v127, v127, v245, vcc
	v_cndmask_b32_e32 v123, v123, v245, vcc
	v_cmp_lt_i32_e32 vcc, s46, v185
	s_movk_i32 s46, 0x71
	s_nop 0
	v_cndmask_b32_e32 v132, v132, v245, vcc
	v_cndmask_b32_e32 v128, v128, v245, vcc
	v_cmp_lt_i32_e32 vcc, s46, v185
	s_movk_i32 s46, 0x72
	s_nop 0
	v_cndmask_b32_e32 v133, v133, v245, vcc
	v_cndmask_b32_e32 v129, v129, v245, vcc
	v_cmp_lt_i32_e32 vcc, s46, v185
	s_movk_i32 s46, 0x73
	s_nop 0
	v_cndmask_b32_e32 v134, v134, v245, vcc
	v_cndmask_b32_e32 v130, v130, v245, vcc
	v_cmp_lt_i32_e32 vcc, s46, v185
	s_movk_i32 s46, 0x80
	s_nop 0
	v_cndmask_b32_e32 v135, v135, v245, vcc
	v_cndmask_b32_e32 v131, v131, v245, vcc
	v_cmp_lt_i32_e32 vcc, s46, v185
	s_movk_i32 s46, 0x81
	s_nop 0
	v_cndmask_b32_e32 v152, v152, v245, vcc
	v_cndmask_b32_e32 v136, v136, v245, vcc
	v_cmp_lt_i32_e32 vcc, s46, v185
	s_movk_i32 s46, 0x82
	s_nop 0
	v_cndmask_b32_e32 v148, v148, v245, vcc
	v_cndmask_b32_e32 v137, v137, v245, vcc
	v_cmp_lt_i32_e32 vcc, s46, v185
	s_movk_i32 s46, 0x83
	s_nop 0
	v_cndmask_b32_e32 v149, v149, v245, vcc
	v_cndmask_b32_e32 v138, v138, v245, vcc
	v_cmp_lt_i32_e32 vcc, s46, v185
	s_movk_i32 s46, 0x91
	s_nop 0
	v_cndmask_b32_e32 v150, v150, v245, vcc
	v_cndmask_b32_e32 v139, v139, v245, vcc
	v_cmp_gt_i32_e32 vcc, s46, v185
	s_movk_i32 s46, 0x92
	s_nop 0
	v_cndmask_b32_e32 v140, v245, v140, vcc
	v_cmp_gt_i32_e32 vcc, s46, v185
	s_movk_i32 s46, 0x93
	s_nop 0
	v_cndmask_b32_e32 v141, v245, v141, vcc
	v_cmp_gt_i32_e32 vcc, s46, v185
	s_movk_i32 s46, 0x94
	s_nop 0
	v_cndmask_b32_e32 v142, v245, v142, vcc
	v_cmp_gt_i32_e32 vcc, s46, v185
	s_nop 1
	v_cndmask_b32_e32 v143, v245, v143, vcc

.LBB0_976:
	s_add_u32 s60, s96, s28
	s_addc_u32 s61, s97, 0
	v_lshl_add_u64 v[152:153], v[160:161], 1, s[60:61]
	s_mov_b64 s[60:61], 0xe000000
	v_lshl_add_u64 v[154:155], v[152:153], 0, s[60:61]
	s_mov_b64 s[60:61], 0x1a000000
	v_lshl_add_u64 v[206:207], v[150:151], 0, s[88:89]
	v_lshl_add_u64 v[152:153], v[152:153], 0, s[60:61]
	v_mad_u64_u32 v[184:185], s[60:61], v206, s20, v[154:155]
	v_mov_b32_e32 v182, v185
	v_lshlrev_b64 v[208:209], 6, v[206:207]
	v_mad_u64_u32 v[182:183], s[60:61], v207, s20, v[182:183]
	v_lshl_add_u64 v[208:209], s[46:47], 0, v[208:209]
	s_lshl_b32 s64, s24, 2
	v_mov_b32_e32 v185, v182
	v_lshl_add_u64 v[208:209], v[208:209], 0, s[64:65]
	global_load_dwordx2 v[214:215], v[184:185], off
	global_load_dwordx2 v[216:217], v[184:185], off offset:2048
	global_load_dwordx2 v[210:211], v[184:185], off offset:32
	global_load_dwordx2 v[212:213], v[184:185], off offset:2080
	global_load_dwordx2 v[202:203], v[184:185], off offset:64
	global_load_dwordx2 v[204:205], v[184:185], off offset:2112
	global_load_dwordx2 v[198:199], v[184:185], off offset:96
	global_load_dwordx2 v[200:201], v[184:185], off offset:2144
	global_load_dwordx2 v[194:195], v[184:185], off offset:128
	global_load_dwordx2 v[196:197], v[184:185], off offset:2176
	global_load_dwordx2 v[190:191], v[184:185], off offset:160
	global_load_dwordx2 v[192:193], v[184:185], off offset:2208
	global_load_dwordx2 v[186:187], v[184:185], off offset:192
	global_load_dwordx2 v[188:189], v[184:185], off offset:2240
	global_load_dwordx2 v[182:183], v[184:185], off offset:224
	s_nop 0
	global_load_dwordx2 v[184:185], v[184:185], off offset:2272
	s_nop 0
	global_load_dword v236, v[208:209], off
	s_nop 0
	global_load_dword v208, v[208:209], off offset:32
	v_div_scale_f32 v209, s[60:61], v246, v246, 1.0
	v_rcp_f32_e32 v237, v209
	v_lshlrev_b64 v[206:207], 11, v[206:207]
	v_lshl_add_u64 v[206:207], v[152:153], 0, v[206:207]
	v_fma_f32 v247, -v209, v237, 1.0
	v_fmac_f32_e32 v237, v247, v237
	v_div_scale_f32 v247, vcc, 1.0, v246, 1.0
	v_mul_f32_e32 v248, v247, v237
	v_fma_f32 v249, -v209, v248, v247
	v_fmac_f32_e32 v248, v249, v237
	v_fma_f32 v209, -v209, v248, v247
	v_div_fmas_f32 v209, v209, v237, v248
	v_div_fixup_f32 v237, v209, v246, 1.0
	v_log_f32_e32 v209, v246
	s_waitcnt vmcnt(0) lgkmcnt(0)
	v_and_b32_e32 v253, 0xffff0000, v214
	v_add_f32_e32 v247, s25, v209
	v_mul_f32_e32 v209, 0x3f317218, v247
	v_max3_f32 v248, v209, v236, v208
	v_sub_f32_e32 v208, v208, v248
	v_sub_f32_e32 v209, v236, v248
	v_mul_f32_e32 v208, 0x3fb8aa3b, v208
	v_mul_f32_e32 v209, 0x3fb8aa3b, v209
	v_exp_f32_e32 v236, v208
	v_fma_f32 v208, v247, s22, -v248
	v_exp_f32_e32 v209, v209
	v_mul_f32_e32 v208, 0x3fb8aa3b, v208
	v_exp_f32_e32 v208, v208
	v_add_f32_e32 v247, v209, v236
	v_add_f32_e32 v247, v208, v247
	v_div_scale_f32 v248, s[60:61], v247, v247, 1.0
	v_rcp_f32_e32 v249, v248
	s_nop 0
	v_fma_f32 v250, -v248, v249, 1.0
	v_fmac_f32_e32 v249, v250, v249
	v_div_scale_f32 v250, vcc, 1.0, v247, 1.0
	v_mul_f32_e32 v251, v250, v249
	v_fma_f32 v252, -v248, v251, v250
	v_fmac_f32_e32 v251, v252, v249
	v_fma_f32 v248, -v248, v251, v250
	v_div_fmas_f32 v248, v248, v249, v251
	v_div_fixup_f32 v249, v248, v247, 1.0
	v_mul_f32_e32 v248, v237, v249
	v_lshlrev_b32_e32 v251, 16, v214
	v_pk_mul_f32 v[208:209], v[208:209], v[248:249]
	v_mov_b32_e32 v250, v120
	v_mul_f32_e32 v247, v236, v249
	v_lshlrev_b32_e32 v236, 16, v216
	v_pk_mul_f32 v[248:249], v[208:209], v[250:251]
	v_mov_b32_e32 v252, v121
	v_fma_f32 v236, v247, v236, v249
	v_and_b32_e32 v214, 0xffff0000, v216
	v_add_f32_e32 v236, v248, v236
	v_pk_mul_f32 v[248:249], v[208:209], v[252:253]
	v_lshlrev_b32_e32 v237, 16, v215
	v_fma_f32 v214, v247, v214, v249
	v_add_f32_e32 v214, v248, v214
	v_cvt_pk_bf16_f32 v214, v236, v214
	v_mov_b32_e32 v236, v122
	v_lshlrev_b32_e32 v216, 16, v217
	v_pk_mul_f32 v[236:237], v[236:237], v[208:209]
	s_nop 0
	v_fma_f32 v216, v247, v216, v237
	v_add_f32_e32 v248, v236, v216
	v_and_b32_e32 v237, 0xffff0000, v215
	v_mov_b32_e32 v236, v123
	v_and_b32_e32 v215, 0xffff0000, v217
	v_pk_mul_f32 v[216:217], v[208:209], v[236:237]
	s_nop 0
	v_fma_f32 v215, v247, v215, v217
	v_add_f32_e32 v215, v216, v215
	v_cvt_pk_bf16_f32 v215, v248, v215
	global_store_dwordx2 v[206:207], v[214:215], off
	v_lshlrev_b32_e32 v215, 16, v210
	v_mov_b32_e32 v214, v116
	v_lshlrev_b32_e32 v216, 16, v212
	v_pk_mul_f32 v[214:215], v[208:209], v[214:215]
	s_nop 0
	v_fma_f32 v215, v247, v216, v215
	v_add_f32_e32 v216, v214, v215
	v_and_b32_e32 v215, 0xffff0000, v210
	v_mov_b32_e32 v214, v117
	v_and_b32_e32 v210, 0xffff0000, v212
	v_pk_mul_f32 v[214:215], v[208:209], v[214:215]
	v_lshlrev_b32_e32 v212, 16, v213
	v_fma_f32 v210, v247, v210, v215
	v_add_f32_e32 v210, v214, v210
	v_lshlrev_b32_e32 v215, 16, v211
	v_mov_b32_e32 v214, v118
	v_pk_mul_f32 v[214:215], v[208:209], v[214:215]
	v_cvt_pk_bf16_f32 v210, v216, v210
	s_nop 0
	v_fma_f32 v212, v247, v212, v215
	v_add_f32_e32 v216, v214, v212
	v_and_b32_e32 v215, 0xffff0000, v211
	v_mov_b32_e32 v214, v119
	v_and_b32_e32 v211, 0xffff0000, v213
	v_pk_mul_f32 v[212:213], v[208:209], v[214:215]
	s_nop 0
	v_fma_f32 v211, v247, v211, v213
	v_add_f32_e32 v211, v212, v211
	v_cvt_pk_bf16_f32 v211, v216, v211
	global_store_dwordx2 v[206:207], v[210:211], off offset:32
	v_lshlrev_b32_e32 v211, 16, v202
	v_mov_b32_e32 v210, v124
	v_lshlrev_b32_e32 v212, 16, v204
	v_pk_mul_f32 v[210:211], v[208:209], v[210:211]
	s_nop 0
	v_fma_f32 v211, v247, v212, v211
	v_add_f32_e32 v212, v210, v211
	v_and_b32_e32 v211, 0xffff0000, v202
	v_mov_b32_e32 v210, v125
	v_and_b32_e32 v202, 0xffff0000, v204
	v_pk_mul_f32 v[210:211], v[208:209], v[210:211]
	v_lshlrev_b32_e32 v204, 16, v205
	v_fma_f32 v202, v247, v202, v211
	v_add_f32_e32 v202, v210, v202
	v_lshlrev_b32_e32 v211, 16, v203
	v_mov_b32_e32 v210, v126
	v_pk_mul_f32 v[210:211], v[208:209], v[210:211]
	v_cvt_pk_bf16_f32 v202, v212, v202
	s_nop 0
	v_fma_f32 v204, v247, v204, v211
	v_add_f32_e32 v212, v210, v204
	v_and_b32_e32 v211, 0xffff0000, v203
	v_mov_b32_e32 v210, v127
	v_and_b32_e32 v203, 0xffff0000, v205
	v_pk_mul_f32 v[204:205], v[208:209], v[210:211]
	s_nop 0
	v_fma_f32 v203, v247, v203, v205
	v_add_f32_e32 v203, v204, v203
	v_cvt_pk_bf16_f32 v203, v212, v203
	global_store_dwordx2 v[206:207], v[202:203], off offset:64
	v_lshlrev_b32_e32 v203, 16, v198
	v_mov_b32_e32 v202, v132
	v_lshlrev_b32_e32 v204, 16, v200
	v_pk_mul_f32 v[202:203], v[208:209], v[202:203]
	s_nop 0
	v_fma_f32 v203, v247, v204, v203
	v_add_f32_e32 v204, v202, v203
	v_and_b32_e32 v203, 0xffff0000, v198
	v_mov_b32_e32 v202, v133
	v_and_b32_e32 v198, 0xffff0000, v200
	v_pk_mul_f32 v[202:203], v[208:209], v[202:203]
	v_lshlrev_b32_e32 v200, 16, v201
	v_fma_f32 v198, v247, v198, v203
	v_add_f32_e32 v198, v202, v198
	v_lshlrev_b32_e32 v203, 16, v199
	v_mov_b32_e32 v202, v134
	v_pk_mul_f32 v[202:203], v[208:209], v[202:203]
	v_cvt_pk_bf16_f32 v198, v204, v198
	s_nop 0
	v_fma_f32 v200, v247, v200, v203
	v_add_f32_e32 v204, v202, v200
	v_and_b32_e32 v203, 0xffff0000, v199
	v_mov_b32_e32 v202, v135
	v_and_b32_e32 v199, 0xffff0000, v201
	v_pk_mul_f32 v[200:201], v[208:209], v[202:203]
	s_nop 0
	v_fma_f32 v199, v247, v199, v201
	v_add_f32_e32 v199, v200, v199
	v_cvt_pk_bf16_f32 v199, v204, v199
	global_store_dwordx2 v[206:207], v[198:199], off offset:96
	v_lshlrev_b32_e32 v199, 16, v194
	v_mov_b32_e32 v198, v128
	v_lshlrev_b32_e32 v200, 16, v196
	v_pk_mul_f32 v[198:199], v[208:209], v[198:199]
	s_nop 0
	v_fma_f32 v199, v247, v200, v199
	v_add_f32_e32 v200, v198, v199
	v_and_b32_e32 v199, 0xffff0000, v194
	v_mov_b32_e32 v198, v129
	v_and_b32_e32 v194, 0xffff0000, v196
	v_pk_mul_f32 v[198:199], v[208:209], v[198:199]
	v_lshlrev_b32_e32 v196, 16, v197
	v_fma_f32 v194, v247, v194, v199
	v_add_f32_e32 v194, v198, v194
	v_lshlrev_b32_e32 v199, 16, v195
	v_mov_b32_e32 v198, v130
	v_pk_mul_f32 v[198:199], v[208:209], v[198:199]
	v_cvt_pk_bf16_f32 v194, v200, v194
	s_nop 0
	v_fma_f32 v196, v247, v196, v199
	v_add_f32_e32 v200, v198, v196
	v_and_b32_e32 v199, 0xffff0000, v195
	v_mov_b32_e32 v198, v131
	v_and_b32_e32 v195, 0xffff0000, v197
	v_pk_mul_f32 v[196:197], v[208:209], v[198:199]
	s_nop 0
	v_fma_f32 v195, v247, v195, v197
	v_add_f32_e32 v195, v196, v195
	v_cvt_pk_bf16_f32 v195, v200, v195
	global_store_dwordx2 v[206:207], v[194:195], off offset:128
	v_lshlrev_b32_e32 v195, 16, v190
	v_mov_b32_e32 v194, v136
	v_lshlrev_b32_e32 v196, 16, v192
	v_pk_mul_f32 v[194:195], v[208:209], v[194:195]
	s_nop 0
	v_fma_f32 v195, v247, v196, v195
	v_add_f32_e32 v196, v194, v195
	v_and_b32_e32 v195, 0xffff0000, v190
	v_mov_b32_e32 v194, v137
	v_and_b32_e32 v190, 0xffff0000, v192
	v_pk_mul_f32 v[194:195], v[208:209], v[194:195]
	v_lshlrev_b32_e32 v192, 16, v193
	v_fma_f32 v190, v247, v190, v195
	v_add_f32_e32 v190, v194, v190
	v_lshlrev_b32_e32 v195, 16, v191
	v_mov_b32_e32 v194, v138
	v_pk_mul_f32 v[194:195], v[208:209], v[194:195]
	v_cvt_pk_bf16_f32 v190, v196, v190
	s_nop 0
	v_fma_f32 v192, v247, v192, v195
	v_add_f32_e32 v196, v194, v192
	v_and_b32_e32 v195, 0xffff0000, v191
	v_mov_b32_e32 v194, v139
	v_and_b32_e32 v191, 0xffff0000, v193
	v_pk_mul_f32 v[192:193], v[208:209], v[194:195]
	s_nop 0
	v_fma_f32 v191, v247, v191, v193
	v_add_f32_e32 v191, v192, v191
	v_cvt_pk_bf16_f32 v191, v196, v191
	global_store_dwordx2 v[206:207], v[190:191], off offset:160
	v_lshlrev_b32_e32 v191, 16, v186
	v_mov_b32_e32 v190, v140
	v_lshlrev_b32_e32 v192, 16, v188
	v_pk_mul_f32 v[190:191], v[208:209], v[190:191]
	s_nop 0
	v_fma_f32 v191, v247, v192, v191
	v_add_f32_e32 v192, v190, v191
	v_and_b32_e32 v191, 0xffff0000, v186
	v_mov_b32_e32 v190, v141
	v_and_b32_e32 v186, 0xffff0000, v188
	v_pk_mul_f32 v[190:191], v[208:209], v[190:191]
	v_lshlrev_b32_e32 v188, 16, v189
	v_fma_f32 v186, v247, v186, v191
	v_add_f32_e32 v186, v190, v186
	v_lshlrev_b32_e32 v191, 16, v187
	v_mov_b32_e32 v190, v142
	v_pk_mul_f32 v[190:191], v[208:209], v[190:191]
	v_cvt_pk_bf16_f32 v186, v192, v186
	s_nop 0
	v_fma_f32 v188, v247, v188, v191
	v_add_f32_e32 v192, v190, v188
	v_and_b32_e32 v191, 0xffff0000, v187
	v_mov_b32_e32 v190, v143
	v_and_b32_e32 v187, 0xffff0000, v189
	v_pk_mul_f32 v[188:189], v[208:209], v[190:191]
	s_nop 0
	v_fma_f32 v187, v247, v187, v189
	v_add_f32_e32 v187, v188, v187
	v_cvt_pk_bf16_f32 v187, v192, v187
	global_store_dwordx2 v[206:207], v[186:187], off offset:192
	v_lshlrev_b32_e32 v187, 16, v182
	v_mov_b32_e32 v186, v144
	v_lshlrev_b32_e32 v188, 16, v184
	v_pk_mul_f32 v[186:187], v[208:209], v[186:187]
	s_nop 0
	v_fma_f32 v187, v247, v188, v187
	v_add_f32_e32 v188, v186, v187
	v_and_b32_e32 v187, 0xffff0000, v182
	v_mov_b32_e32 v186, v145
	v_and_b32_e32 v182, 0xffff0000, v184
	v_pk_mul_f32 v[186:187], v[208:209], v[186:187]
	v_lshlrev_b32_e32 v184, 16, v185
	v_fma_f32 v182, v247, v182, v187
	v_add_f32_e32 v182, v186, v182
	v_lshlrev_b32_e32 v187, 16, v183
	v_mov_b32_e32 v186, v146
	v_pk_mul_f32 v[186:187], v[208:209], v[186:187]
	v_cvt_pk_bf16_f32 v182, v188, v182
	s_nop 0
	v_fma_f32 v184, v247, v184, v187
	v_add_f32_e32 v188, v186, v184
	v_and_b32_e32 v187, 0xffff0000, v183
	v_mov_b32_e32 v186, v147
	v_and_b32_e32 v183, 0xffff0000, v185
	v_pk_mul_f32 v[184:185], v[208:209], v[186:187]
	s_nop 0
	v_fma_f32 v183, v247, v183, v185
	v_add_f32_e32 v183, v184, v183
	v_cvt_pk_bf16_f32 v183, v188, v183
	global_store_dwordx2 v[206:207], v[182:183], off offset:224
	v_lshlrev_b64 v[182:183], s23, v[148:149]
	v_lshl_add_u64 v[212:213], v[182:183], 0, s[88:89]
	v_mad_u64_u32 v[182:183], s[60:61], v212, s20, v[154:155]
	v_mov_b32_e32 v154, v183
	v_lshlrev_b64 v[214:215], 6, v[212:213]
	v_mad_u64_u32 v[154:155], s[60:61], v213, s20, v[154:155]
	v_lshl_add_u64 v[214:215], s[46:47], 0, v[214:215]
	v_mov_b32_e32 v183, v154
	v_lshl_add_u64 v[214:215], v[214:215], 0, s[64:65]
	global_load_dwordx2 v[208:209], v[182:183], off
	global_load_dwordx2 v[210:211], v[182:183], off offset:2048
	global_load_dwordx2 v[204:205], v[182:183], off offset:32
	global_load_dwordx2 v[206:207], v[182:183], off offset:2080
	global_load_dwordx2 v[200:201], v[182:183], off offset:64
	global_load_dwordx2 v[202:203], v[182:183], off offset:2112
	global_load_dwordx2 v[196:197], v[182:183], off offset:96
	global_load_dwordx2 v[198:199], v[182:183], off offset:2144
	global_load_dwordx2 v[192:193], v[182:183], off offset:128
	global_load_dwordx2 v[194:195], v[182:183], off offset:2176
	global_load_dwordx2 v[188:189], v[182:183], off offset:160
	global_load_dwordx2 v[190:191], v[182:183], off offset:2208
	global_load_dwordx2 v[184:185], v[182:183], off offset:192
	global_load_dwordx2 v[186:187], v[182:183], off offset:2240
	global_load_dwordx2 v[154:155], v[182:183], off offset:224
	s_nop 0
	global_load_dwordx2 v[182:183], v[182:183], off offset:2272
	s_nop 0
	global_load_dword v216, v[214:215], off
	s_nop 0
	global_load_dword v214, v[214:215], off offset:32
	v_div_scale_f32 v215, s[60:61], v167, v167, 1.0
	v_rcp_f32_e32 v217, v215
	v_lshlrev_b64 v[212:213], 11, v[212:213]
	v_lshl_add_u64 v[152:153], v[152:153], 0, v[212:213]
	v_fma_f32 v236, -v215, v217, 1.0
	v_fmac_f32_e32 v217, v236, v217
	v_div_scale_f32 v236, vcc, 1.0, v167, 1.0
	v_mul_f32_e32 v237, v236, v217
	v_fma_f32 v247, -v215, v237, v236
	v_fmac_f32_e32 v237, v247, v217
	v_fma_f32 v215, -v215, v237, v236
	v_div_fmas_f32 v215, v215, v217, v237
	v_div_fixup_f32 v236, v215, v167, 1.0
	v_log_f32_e32 v215, v167
	s_waitcnt vmcnt(0) lgkmcnt(0)
	v_lshlrev_b32_e32 v251, 16, v209
	v_add_f32_e32 v217, s25, v215
	v_mul_f32_e32 v215, 0x3f317218, v217
	v_max3_f32 v237, v215, v216, v214
	v_sub_f32_e32 v214, v214, v237
	v_sub_f32_e32 v215, v216, v237
	v_mul_f32_e32 v214, 0x3fb8aa3b, v214
	v_mul_f32_e32 v215, 0x3fb8aa3b, v215
	v_exp_f32_e32 v216, v214
	v_fma_f32 v214, v217, s22, -v237
	v_exp_f32_e32 v215, v215
	v_mul_f32_e32 v214, 0x3fb8aa3b, v214
	v_exp_f32_e32 v214, v214
	v_add_f32_e32 v217, v215, v216
	v_add_f32_e32 v217, v214, v217
	v_div_scale_f32 v237, s[60:61], v217, v217, 1.0
	v_rcp_f32_e32 v247, v237
	s_nop 0
	v_fma_f32 v248, -v237, v247, 1.0
	v_fmac_f32_e32 v247, v248, v247
	v_div_scale_f32 v248, vcc, 1.0, v217, 1.0
	v_mul_f32_e32 v249, v248, v247
	v_fma_f32 v250, -v237, v249, v248
	v_fmac_f32_e32 v249, v250, v247
	v_fma_f32 v237, -v237, v249, v248
	v_div_fmas_f32 v237, v237, v247, v249
	v_div_fixup_f32 v217, v237, v217, 1.0
	v_mul_f32_e32 v247, v216, v217
	v_mul_f32_e32 v216, v236, v217
	v_lshlrev_b32_e32 v237, 16, v208
	v_pk_mul_f32 v[212:213], v[214:215], v[216:217]
	v_mov_b32_e32 v236, v88
	v_lshlrev_b32_e32 v248, 16, v210
	v_pk_mul_f32 v[214:215], v[212:213], v[236:237]
	v_and_b32_e32 v249, 0xffff0000, v208
	v_fma_f32 v215, v247, v248, v215
	v_mov_b32_e32 v248, v89
	v_and_b32_e32 v208, 0xffff0000, v210
	v_add_f32_e32 v216, v214, v215
	v_pk_mul_f32 v[214:215], v[212:213], v[248:249]
	v_mov_b32_e32 v250, v90
	v_fma_f32 v208, v247, v208, v215
	v_lshlrev_b32_e32 v210, 16, v211
	v_add_f32_e32 v208, v214, v208
	v_pk_mul_f32 v[214:215], v[250:251], v[212:213]
	v_cvt_pk_bf16_f32 v208, v216, v208
	s_nop 0
	v_fma_f32 v210, v247, v210, v215
	v_add_f32_e32 v216, v214, v210
	v_and_b32_e32 v215, 0xffff0000, v209
	v_mov_b32_e32 v214, v91
	v_and_b32_e32 v209, 0xffff0000, v211
	v_pk_mul_f32 v[210:211], v[212:213], v[214:215]
	s_nop 0
	v_fma_f32 v209, v247, v209, v211
	v_add_f32_e32 v209, v210, v209
	v_cvt_pk_bf16_f32 v209, v216, v209
	global_store_dwordx2 v[152:153], v[208:209], off
	v_lshlrev_b32_e32 v209, 16, v204
	v_mov_b32_e32 v208, v84
	v_lshlrev_b32_e32 v210, 16, v206
	v_pk_mul_f32 v[208:209], v[212:213], v[208:209]
	s_nop 0
	v_fma_f32 v209, v247, v210, v209
	v_add_f32_e32 v210, v208, v209
	v_and_b32_e32 v209, 0xffff0000, v204
	v_mov_b32_e32 v208, v85
	v_and_b32_e32 v204, 0xffff0000, v206
	v_pk_mul_f32 v[208:209], v[212:213], v[208:209]
	v_lshlrev_b32_e32 v206, 16, v207
	v_fma_f32 v204, v247, v204, v209
	v_add_f32_e32 v204, v208, v204
	v_lshlrev_b32_e32 v209, 16, v205
	v_mov_b32_e32 v208, v86
	v_pk_mul_f32 v[208:209], v[212:213], v[208:209]
	v_cvt_pk_bf16_f32 v204, v210, v204
	s_nop 0
	v_fma_f32 v206, v247, v206, v209
	v_add_f32_e32 v210, v208, v206
	v_and_b32_e32 v209, 0xffff0000, v205
	v_mov_b32_e32 v208, v87
	v_and_b32_e32 v205, 0xffff0000, v207
	v_pk_mul_f32 v[206:207], v[212:213], v[208:209]
	s_nop 0
	v_fma_f32 v205, v247, v205, v207
	v_add_f32_e32 v205, v206, v205
	v_cvt_pk_bf16_f32 v205, v210, v205
	global_store_dwordx2 v[152:153], v[204:205], off offset:32
	v_lshlrev_b32_e32 v205, 16, v200
	v_mov_b32_e32 v204, v92
	v_lshlrev_b32_e32 v206, 16, v202
	v_pk_mul_f32 v[204:205], v[212:213], v[204:205]
	s_nop 0
	v_fma_f32 v205, v247, v206, v205
	v_add_f32_e32 v206, v204, v205
	v_and_b32_e32 v205, 0xffff0000, v200
	v_mov_b32_e32 v204, v93
	v_and_b32_e32 v200, 0xffff0000, v202
	v_pk_mul_f32 v[204:205], v[212:213], v[204:205]
	v_lshlrev_b32_e32 v202, 16, v203
	v_fma_f32 v200, v247, v200, v205
	v_add_f32_e32 v200, v204, v200
	v_lshlrev_b32_e32 v205, 16, v201
	v_mov_b32_e32 v204, v94
	v_pk_mul_f32 v[204:205], v[212:213], v[204:205]
	v_cvt_pk_bf16_f32 v200, v206, v200
	s_nop 0
	v_fma_f32 v202, v247, v202, v205
	v_add_f32_e32 v206, v204, v202
	v_and_b32_e32 v205, 0xffff0000, v201
	v_mov_b32_e32 v204, v95
	v_and_b32_e32 v201, 0xffff0000, v203
	v_pk_mul_f32 v[202:203], v[212:213], v[204:205]
	s_nop 0
	v_fma_f32 v201, v247, v201, v203
	v_add_f32_e32 v201, v202, v201
	v_cvt_pk_bf16_f32 v201, v206, v201
	global_store_dwordx2 v[152:153], v[200:201], off offset:64
	v_lshlrev_b32_e32 v201, 16, v196
	v_mov_b32_e32 v200, v100
	v_lshlrev_b32_e32 v202, 16, v198
	v_pk_mul_f32 v[200:201], v[212:213], v[200:201]
	s_nop 0
	v_fma_f32 v201, v247, v202, v201
	v_add_f32_e32 v202, v200, v201
	v_and_b32_e32 v201, 0xffff0000, v196
	v_mov_b32_e32 v200, v101
	v_and_b32_e32 v196, 0xffff0000, v198
	v_pk_mul_f32 v[200:201], v[212:213], v[200:201]
	v_lshlrev_b32_e32 v198, 16, v199
	v_fma_f32 v196, v247, v196, v201
	v_add_f32_e32 v196, v200, v196
	v_lshlrev_b32_e32 v201, 16, v197
	v_mov_b32_e32 v200, v102
	v_pk_mul_f32 v[200:201], v[212:213], v[200:201]
	v_cvt_pk_bf16_f32 v196, v202, v196
	s_nop 0
	v_fma_f32 v198, v247, v198, v201
	v_add_f32_e32 v202, v200, v198
	v_and_b32_e32 v201, 0xffff0000, v197
	v_mov_b32_e32 v200, v103
	v_and_b32_e32 v197, 0xffff0000, v199
	v_pk_mul_f32 v[198:199], v[212:213], v[200:201]
	s_nop 0
	v_fma_f32 v197, v247, v197, v199
	v_add_f32_e32 v197, v198, v197
	v_cvt_pk_bf16_f32 v197, v202, v197
	global_store_dwordx2 v[152:153], v[196:197], off offset:96
	v_lshlrev_b32_e32 v197, 16, v192
	v_mov_b32_e32 v196, v96
	v_lshlrev_b32_e32 v198, 16, v194
	v_pk_mul_f32 v[196:197], v[212:213], v[196:197]
	s_nop 0
	v_fma_f32 v197, v247, v198, v197
	v_add_f32_e32 v198, v196, v197
	v_and_b32_e32 v197, 0xffff0000, v192
	v_mov_b32_e32 v196, v97
	v_and_b32_e32 v192, 0xffff0000, v194
	v_pk_mul_f32 v[196:197], v[212:213], v[196:197]
	v_lshlrev_b32_e32 v194, 16, v195
	v_fma_f32 v192, v247, v192, v197
	v_add_f32_e32 v192, v196, v192
	v_lshlrev_b32_e32 v197, 16, v193
	v_mov_b32_e32 v196, v98
	v_pk_mul_f32 v[196:197], v[212:213], v[196:197]
	v_cvt_pk_bf16_f32 v192, v198, v192
	s_nop 0
	v_fma_f32 v194, v247, v194, v197
	v_add_f32_e32 v198, v196, v194
	v_and_b32_e32 v197, 0xffff0000, v193
	v_mov_b32_e32 v196, v99
	v_and_b32_e32 v193, 0xffff0000, v195
	v_pk_mul_f32 v[194:195], v[212:213], v[196:197]
	s_nop 0
	v_fma_f32 v193, v247, v193, v195
	v_add_f32_e32 v193, v194, v193
	v_cvt_pk_bf16_f32 v193, v198, v193
	global_store_dwordx2 v[152:153], v[192:193], off offset:128
	v_lshlrev_b32_e32 v193, 16, v188
	v_mov_b32_e32 v192, v104
	v_lshlrev_b32_e32 v194, 16, v190
	v_pk_mul_f32 v[192:193], v[212:213], v[192:193]
	s_nop 0
	v_fma_f32 v193, v247, v194, v193
	v_add_f32_e32 v194, v192, v193
	v_and_b32_e32 v193, 0xffff0000, v188
	v_mov_b32_e32 v192, v105
	v_and_b32_e32 v188, 0xffff0000, v190
	v_pk_mul_f32 v[192:193], v[212:213], v[192:193]
	v_lshlrev_b32_e32 v190, 16, v191
	v_fma_f32 v188, v247, v188, v193
	v_add_f32_e32 v188, v192, v188
	v_lshlrev_b32_e32 v193, 16, v189
	v_mov_b32_e32 v192, v106
	v_pk_mul_f32 v[192:193], v[212:213], v[192:193]
	v_cvt_pk_bf16_f32 v188, v194, v188
	s_nop 0
	v_fma_f32 v190, v247, v190, v193
	v_add_f32_e32 v194, v192, v190
	v_and_b32_e32 v193, 0xffff0000, v189
	v_mov_b32_e32 v192, v107
	v_and_b32_e32 v189, 0xffff0000, v191
	v_pk_mul_f32 v[190:191], v[212:213], v[192:193]
	s_nop 0
	v_fma_f32 v189, v247, v189, v191
	v_add_f32_e32 v189, v190, v189
	v_cvt_pk_bf16_f32 v189, v194, v189
	global_store_dwordx2 v[152:153], v[188:189], off offset:160
	v_lshlrev_b32_e32 v189, 16, v184
	v_mov_b32_e32 v188, v108
	v_lshlrev_b32_e32 v190, 16, v186
	v_pk_mul_f32 v[188:189], v[212:213], v[188:189]
	s_nop 0
	v_fma_f32 v189, v247, v190, v189
	v_add_f32_e32 v190, v188, v189
	v_and_b32_e32 v189, 0xffff0000, v184
	v_mov_b32_e32 v188, v109
	v_and_b32_e32 v184, 0xffff0000, v186
	v_pk_mul_f32 v[188:189], v[212:213], v[188:189]
	v_lshlrev_b32_e32 v186, 16, v187
	v_fma_f32 v184, v247, v184, v189
	v_add_f32_e32 v184, v188, v184
	v_lshlrev_b32_e32 v189, 16, v185
	v_mov_b32_e32 v188, v110
	v_pk_mul_f32 v[188:189], v[212:213], v[188:189]
	v_cvt_pk_bf16_f32 v184, v190, v184
	s_nop 0
	v_fma_f32 v186, v247, v186, v189
	v_add_f32_e32 v190, v188, v186
	v_and_b32_e32 v189, 0xffff0000, v185
	v_mov_b32_e32 v188, v111
	v_and_b32_e32 v185, 0xffff0000, v187
	v_pk_mul_f32 v[186:187], v[212:213], v[188:189]
	s_nop 0
	v_fma_f32 v185, v247, v185, v187
	v_add_f32_e32 v185, v186, v185
	v_cvt_pk_bf16_f32 v185, v190, v185
	global_store_dwordx2 v[152:153], v[184:185], off offset:192
	v_lshlrev_b32_e32 v185, 16, v154
	v_mov_b32_e32 v184, v112
	v_lshlrev_b32_e32 v186, 16, v182
	v_pk_mul_f32 v[184:185], v[212:213], v[184:185]
	s_nop 0
	v_fma_f32 v185, v247, v186, v185
	v_add_f32_e32 v186, v184, v185
	v_and_b32_e32 v185, 0xffff0000, v154
	v_mov_b32_e32 v184, v113
	v_and_b32_e32 v154, 0xffff0000, v182
	v_pk_mul_f32 v[184:185], v[212:213], v[184:185]
	v_lshlrev_b32_e32 v182, 16, v183
	v_fma_f32 v154, v247, v154, v185
	v_add_f32_e32 v154, v184, v154
	v_lshlrev_b32_e32 v185, 16, v155
	v_mov_b32_e32 v184, v114
	v_pk_mul_f32 v[184:185], v[212:213], v[184:185]
	v_cvt_pk_bf16_f32 v154, v186, v154
	s_nop 0
	v_fma_f32 v182, v247, v182, v185
	v_add_f32_e32 v186, v184, v182
	v_and_b32_e32 v185, 0xffff0000, v155
	v_mov_b32_e32 v184, v115
	v_and_b32_e32 v155, 0xffff0000, v183
	v_pk_mul_f32 v[182:183], v[212:213], v[184:185]
	s_nop 0
	v_fma_f32 v155, v247, v155, v183
	v_add_f32_e32 v155, v182, v155
	v_cvt_pk_bf16_f32 v155, v186, v155
	global_store_dwordx2 v[152:153], v[154:155], off offset:224
	s_cbranch_execnz .LBB0_975
.LBB0_977:
	s_add_u32 s60, s46, s94
	s_addc_u32 s61, s47, s95
	v_div_scale_f32 v152, s[46:47], v246, v246, 1.0
	v_rcp_f32_e32 v153, v152
	s_lshl_b32 s46, s24, 2
	s_add_u32 s46, s60, s46
	v_lshl_add_u64 v[150:151], v[150:151], 0, s[88:89]
	v_fma_f32 v154, -v152, v153, 1.0
	v_fmac_f32_e32 v153, v154, v153
	v_div_scale_f32 v154, vcc, 1.0, v246, 1.0
	v_mul_f32_e32 v155, v154, v153
	v_fma_f32 v182, -v152, v155, v154
	v_fmac_f32_e32 v155, v182, v153
	v_fma_f32 v152, -v152, v155, v154
	v_div_fmas_f32 v152, v152, v153, v155
	v_div_fixup_f32 v182, v152, v246, 1.0
	s_addc_u32 s47, s61, 0
	v_mad_u64_u32 v[152:153], s[60:61], v150, s20, v[178:179]
	v_mul_f32_e32 v120, v120, v182
	v_mul_f32_e32 v121, v121, v182
	v_mov_b32_e32 v154, v153
	v_cvt_pk_bf16_f32 v120, v120, v121
	v_mul_f32_e32 v121, v122, v182
	v_mul_f32_e32 v122, v123, v182
	v_mul_f32_e32 v116, v116, v182
	v_mul_f32_e32 v117, v117, v182
	v_mad_u64_u32 v[154:155], s[60:61], v151, s20, v[154:155]
	v_cvt_pk_bf16_f32 v121, v121, v122
	v_cvt_pk_bf16_f32 v122, v116, v117
	v_mul_f32_e32 v116, v118, v182
	v_mul_f32_e32 v117, v119, v182
	v_cvt_pk_bf16_f32 v123, v116, v117
	v_mov_b32_e32 v153, v154
	v_permlane16_swap_b32_e32 v120, v122
	v_permlane16_swap_b32_e32 v121, v123
	v_mul_f32_e32 v116, v124, v182
	v_mul_f32_e32 v117, v125, v182
	global_store_dwordx4 v[152:153], v[120:123], off
	v_cvt_pk_bf16_f32 v116, v116, v117
	v_mul_f32_e32 v117, v126, v182
	v_mul_f32_e32 v118, v127, v182
	v_cvt_pk_bf16_f32 v117, v117, v118
	v_mul_f32_e32 v118, v132, v182
	v_mul_f32_e32 v119, v133, v182
	v_cvt_pk_bf16_f32 v118, v118, v119
	v_mul_f32_e32 v119, v134, v182
	v_mul_f32_e32 v120, v135, v182
	v_cvt_pk_bf16_f32 v119, v119, v120
	v_permlane16_swap_b32_e32 v116, v118
	v_permlane16_swap_b32_e32 v117, v119
	global_store_dwordx4 v[152:153], v[116:119], off offset:64
	v_mul_f32_e32 v120, v139, v182
	s_nop 0
	v_mul_f32_e32 v116, v128, v182
	v_mul_f32_e32 v117, v129, v182
	v_cvt_pk_bf16_f32 v116, v116, v117
	v_mul_f32_e32 v117, v130, v182
	v_mul_f32_e32 v118, v131, v182
	v_cvt_pk_bf16_f32 v117, v117, v118
	v_mul_f32_e32 v118, v136, v182
	v_mul_f32_e32 v119, v137, v182
	v_cvt_pk_bf16_f32 v118, v118, v119
	v_mul_f32_e32 v119, v138, v182
	v_cvt_pk_bf16_f32 v119, v119, v120
	v_permlane16_swap_b32_e32 v116, v118
	s_nop 0
	v_permlane16_swap_b32_e32 v117, v119
	global_store_dwordx4 v[152:153], v[116:119], off offset:128
	v_mul_f32_e32 v120, v147, v182
	s_nop 0
	v_mul_f32_e32 v116, v140, v182
	v_mul_f32_e32 v117, v141, v182
	v_cvt_pk_bf16_f32 v116, v116, v117
	v_mul_f32_e32 v117, v142, v182
	v_mul_f32_e32 v118, v143, v182
	v_cvt_pk_bf16_f32 v117, v117, v118
	v_mul_f32_e32 v118, v144, v182
	v_mul_f32_e32 v119, v145, v182
	v_cvt_pk_bf16_f32 v118, v118, v119
	v_mul_f32_e32 v119, v146, v182
	v_cvt_pk_bf16_f32 v119, v119, v120
	v_permlane16_swap_b32_e32 v116, v118
	s_nop 0
	v_permlane16_swap_b32_e32 v117, v119
	global_store_dwordx4 v[152:153], v[116:119], off offset:192
	s_and_saveexec_b64 s[60:61], s[6:7]
	s_cbranch_execz .LBB0_979
	v_log_f32_e32 v118, v246
	v_lshlrev_b64 v[116:117], 6, v[150:151]
	v_lshl_add_u64 v[116:117], s[46:47], 0, v[116:117]
	v_add_f32_e32 v118, s25, v118
	v_mul_f32_e32 v118, 0x3f317218, v118
	global_store_dword v[116:117], v118, off
.LBB0_979:
	s_or_b64 exec, exec, s[60:61]
	v_div_scale_f32 v116, s[60:61], v167, v167, 1.0
	v_rcp_f32_e32 v117, v116
	v_div_scale_f32 v118, vcc, 1.0, v167, 1.0
	v_fma_f32 v119, -v116, v117, 1.0
	v_fmac_f32_e32 v117, v119, v117
	v_mul_f32_e32 v119, v118, v117
	v_fma_f32 v120, -v116, v119, v118
	v_fmac_f32_e32 v119, v120, v117
	v_fma_f32 v116, -v116, v119, v118
	v_div_fmas_f32 v116, v116, v117, v119
	v_div_fixup_f32 v122, v116, v167, 1.0
	v_lshlrev_b64 v[116:117], s23, v[148:149]
	v_lshl_add_u64 v[116:117], v[116:117], 0, s[88:89]
	v_mad_u64_u32 v[118:119], s[60:61], v116, s20, v[178:179]
	v_mul_f32_e32 v88, v88, v122
	v_mul_f32_e32 v89, v89, v122
	v_mov_b32_e32 v120, v119
	v_cvt_pk_bf16_f32 v88, v88, v89
	v_mul_f32_e32 v89, v90, v122
	v_mul_f32_e32 v90, v91, v122
	v_mul_f32_e32 v84, v84, v122
	v_mul_f32_e32 v85, v85, v122
	v_mad_u64_u32 v[120:121], s[60:61], v117, s20, v[120:121]
	v_cvt_pk_bf16_f32 v89, v89, v90
	v_cvt_pk_bf16_f32 v90, v84, v85
	v_mul_f32_e32 v84, v86, v122
	v_mul_f32_e32 v85, v87, v122
	v_cvt_pk_bf16_f32 v91, v84, v85
	v_mov_b32_e32 v119, v120
	v_permlane16_swap_b32_e32 v88, v90
	v_permlane16_swap_b32_e32 v89, v91
	v_mul_f32_e32 v84, v92, v122
	v_mul_f32_e32 v85, v93, v122
	global_store_dwordx4 v[118:119], v[88:91], off
	v_cvt_pk_bf16_f32 v84, v84, v85
	v_mul_f32_e32 v85, v94, v122
	v_mul_f32_e32 v86, v95, v122
	v_cvt_pk_bf16_f32 v85, v85, v86
	v_mul_f32_e32 v86, v100, v122
	v_mul_f32_e32 v87, v101, v122
	v_cvt_pk_bf16_f32 v86, v86, v87
	v_mul_f32_e32 v87, v102, v122
	v_mul_f32_e32 v88, v103, v122
	v_cvt_pk_bf16_f32 v87, v87, v88
	v_permlane16_swap_b32_e32 v84, v86
	v_permlane16_swap_b32_e32 v85, v87
	global_store_dwordx4 v[118:119], v[84:87], off offset:64
	v_mul_f32_e32 v88, v107, v122
	s_nop 0
	v_mul_f32_e32 v84, v96, v122
	v_mul_f32_e32 v85, v97, v122
	v_cvt_pk_bf16_f32 v84, v84, v85
	v_mul_f32_e32 v85, v98, v122
	v_mul_f32_e32 v86, v99, v122
	v_cvt_pk_bf16_f32 v85, v85, v86
	v_mul_f32_e32 v86, v104, v122
	v_mul_f32_e32 v87, v105, v122
	v_cvt_pk_bf16_f32 v86, v86, v87
	v_mul_f32_e32 v87, v106, v122
	v_cvt_pk_bf16_f32 v87, v87, v88
	v_permlane16_swap_b32_e32 v84, v86
	s_nop 0
	v_permlane16_swap_b32_e32 v85, v87
	global_store_dwordx4 v[118:119], v[84:87], off offset:128
	v_mul_f32_e32 v88, v115, v122
	s_nop 0
	v_mul_f32_e32 v84, v108, v122
	v_mul_f32_e32 v85, v109, v122
	v_cvt_pk_bf16_f32 v84, v84, v85
	v_mul_f32_e32 v85, v110, v122
	v_mul_f32_e32 v86, v111, v122
	v_cvt_pk_bf16_f32 v85, v85, v86
	v_mul_f32_e32 v86, v112, v122
	v_mul_f32_e32 v87, v113, v122
	v_cvt_pk_bf16_f32 v86, v86, v87
	v_mul_f32_e32 v87, v114, v122
	v_cvt_pk_bf16_f32 v87, v87, v88
	v_permlane16_swap_b32_e32 v84, v86
	s_nop 0
	v_permlane16_swap_b32_e32 v85, v87
	global_store_dwordx4 v[118:119], v[84:87], off offset:192
	s_and_saveexec_b64 s[60:61], s[6:7]
	s_cbranch_execz .LBB0_981
	v_log_f32_e32 v86, v167
	v_lshlrev_b64 v[84:85], 6, v[116:117]
	v_lshl_add_u64 v[84:85], s[46:47], 0, v[84:85]
	v_add_f32_e32 v86, s25, v86
	v_mul_f32_e32 v86, 0x3f317218, v86
	global_store_dword v[84:85], v86, off

.LBB0_982:
	s_waitcnt vmcnt(8)
.Lattn_ring:
	v_mov_b64_e32 v[66:67], v[34:35]
	v_mov_b64_e32 v[54:55], v[30:31]
	v_mov_b64_e32 v[58:59], v[26:27]
	v_mov_b64_e32 v[62:63], v[22:23]
	v_mov_b64_e32 v[70:71], v[50:51]
	v_mov_b64_e32 v[74:75], v[46:47]
	v_mov_b64_e32 v[78:79], v[42:43]
	v_mov_b64_e32 v[82:83], v[38:39]
	v_mov_b64_e32 v[64:65], v[32:33]
	v_mov_b64_e32 v[52:53], v[28:29]
	v_mov_b64_e32 v[56:57], v[24:25]
	v_mov_b64_e32 v[60:61], v[20:21]
	v_mov_b64_e32 v[68:69], v[48:49]
	v_mov_b64_e32 v[72:73], v[44:45]
	v_mov_b64_e32 v[76:77], v[40:41]
	v_mov_b64_e32 v[80:81], v[36:37]
	s_add_i32 s46, s29, 1
	s_and_b32 s46, s46, 3
	s_mul_i32 s46, s46, 0x8c00
	v_add_u32_e32 v20, s46, v223
	v_add_u32_e32 v21, v20, v222
	v_add_u32_e32 v20, v20, v221
	ds_write_b128 v20, v[4:7]
	ds_write_b128 v21, v[8:11] offset:17408
	ds_write_b128 v20, v[12:15] offset:8704
	ds_write_b128 v21, v[16:19] offset:26624
	s_branch .LBB0_966
